# sample-path attention loop: LDS fragment reads software-pipelined too (6 K + 8 V buffers); prompt loop DMA issue spread inside the S phase
# speedup vs baseline: 1.0147x; 1.0147x over previous
.LBB0_972:
	s_mul_i32 s1, s52, 0xa000
	s_waitcnt lgkmcnt(0)
	s_barrier
	v_cmp_le_i32_e32 vcc, s0, v165
	s_and_saveexec_b64 s[36:37], vcc
	s_cbranch_execz .Lpa_masked
	v_add_u32_e32 v6, s1, v176
	v_readfirstlane_b32 vcc_lo, v170
	s_add_i32 s1, s1, 0xffff6000
	s_cmp_lg_u32 s52, 0
	s_cselect_b32 s1, s1, 0x14000
	v_add_u32_e32 v14, v6, v172
	ds_read_b128 v[182:185], v14
	ds_read_b128 v[186:189], v14 offset:4096
	v_add_u32_e32 v15, v6, v173
	ds_read_b128 v[190:193], v15
	ds_read_b128 v[194:197], v15 offset:4096
	v_add_u32_e32 v180, v6, v174
	ds_read_b128 v[198:201], v180
	ds_read_b128 v[202:205], v180 offset:4096
	v_add_u32_e32 v181, v6, v175
	ds_read_b128 v[206:209], v181
	ds_read_b128 v[210:213], v181 offset:4096
	s_add_i32 s1, s1, vcc_lo
	v_xor_b32_e32 v80, 0x80000000, v179
	v_mov_b32_e32 v81, v80
	v_mov_b32_e32 v82, v80
	v_mov_b32_e32 v83, v80
	v_mov_b32_e32 v84, v80
	v_mov_b32_e32 v85, v80
	v_mov_b32_e32 v86, v80
	v_mov_b32_e32 v87, v80
	v_mov_b32_e32 v88, v80
	v_mov_b32_e32 v89, v80
	v_mov_b32_e32 v90, v80
	v_mov_b32_e32 v91, v80
	v_mov_b32_e32 v92, v80
	v_mov_b32_e32 v93, v80
	v_mov_b32_e32 v94, v80
	v_mov_b32_e32 v95, v80
	s_nop 1
	s_waitcnt lgkmcnt(7)
	v_mfma_f32_32x32x16_bf16 v[96:111], v[182:185], v[112:115], v[80:95]
	ds_read_b128 v[182:185], v14 offset:8192
	s_waitcnt lgkmcnt(7)
	v_mfma_f32_32x32x16_bf16 v[80:95], v[186:189], v[112:115], v[80:95]
	ds_read_b128 v[186:189], v14 offset:12288
	s_waitcnt lgkmcnt(7)
	v_mfma_f32_32x32x16_bf16 v[96:111], v[190:193], v[116:119], v[96:111]
	ds_read_b128 v[190:193], v15 offset:8192
	s_cmp_ge_i32 s0, s51
	s_cbranch_scc1 .Lpa_nd0
	s_mov_b32 m0, s1
	s_nop 0
	global_load_lds_dwordx4 v0, s[30:31]
.Lpa_nd0:
	s_waitcnt lgkmcnt(7)
	v_mfma_f32_32x32x16_bf16 v[80:95], v[194:197], v[116:119], v[80:95]
	ds_read_b128 v[194:197], v15 offset:12288
	s_waitcnt lgkmcnt(7)
	v_mfma_f32_32x32x16_bf16 v[96:111], v[198:201], v[120:123], v[96:111]
	ds_read_b128 v[198:201], v180 offset:8192
	s_waitcnt lgkmcnt(7)
	v_mfma_f32_32x32x16_bf16 v[80:95], v[202:205], v[120:123], v[80:95]
	ds_read_b128 v[202:205], v180 offset:12288
	s_waitcnt lgkmcnt(7)
	v_mfma_f32_32x32x16_bf16 v[96:111], v[206:209], v[124:127], v[96:111]
	ds_read_b128 v[206:209], v181 offset:8192
	s_cmp_ge_i32 s0, s51
	s_cbranch_scc1 .Lpa_nd1
	v_lshl_add_u64 v[2:3], s[30:31], 0, v[0:1]
	s_add_i32 m0, s1, 0x2000
	v_lshl_add_u64 v[2:3], v[2:3], 0, s[54:55]
	v_add_u32_e32 v0, 0x20000, v0
	global_load_lds_dwordx4 v[2:3], off
.Lpa_nd1:
	s_waitcnt lgkmcnt(7)
	v_mfma_f32_32x32x16_bf16 v[80:95], v[210:213], v[124:127], v[80:95]
	ds_read_b128 v[210:213], v181 offset:12288
	s_waitcnt lgkmcnt(7)
	v_mfma_f32_32x32x16_bf16 v[96:111], v[182:185], v[128:131], v[96:111]
	ds_read_b128 v[182:185], v14 offset:16384
	s_waitcnt lgkmcnt(7)
	v_mfma_f32_32x32x16_bf16 v[80:95], v[186:189], v[128:131], v[80:95]
	ds_read_b128 v[186:189], v14 offset:20480
	s_waitcnt lgkmcnt(7)
	v_mfma_f32_32x32x16_bf16 v[96:111], v[190:193], v[132:135], v[96:111]
	ds_read_b128 v[190:193], v15 offset:16384
	s_cmp_ge_i32 s0, s51
	s_cbranch_scc1 .Lpa_nd2
	s_add_i32 m0, s1, 0x4000
	s_nop 0
	global_load_lds_dwordx4 v177, s[12:13]
	v_add_u32_e32 v177, 0x2000, v177
.Lpa_nd2:
	s_waitcnt lgkmcnt(7)
	v_mfma_f32_32x32x16_bf16 v[80:95], v[194:197], v[132:135], v[80:95]
	ds_read_b128 v[194:197], v15 offset:20480
	s_waitcnt lgkmcnt(7)
	v_mfma_f32_32x32x16_bf16 v[96:111], v[198:201], v[136:139], v[96:111]
	ds_read_b128 v[198:201], v180 offset:16384
	s_waitcnt lgkmcnt(7)
	v_mfma_f32_32x32x16_bf16 v[80:95], v[202:205], v[136:139], v[80:95]
	ds_read_b128 v[202:205], v180 offset:20480
	s_waitcnt lgkmcnt(7)
	v_mfma_f32_32x32x16_bf16 v[96:111], v[206:209], v[140:143], v[96:111]
	ds_read_b128 v[206:209], v181 offset:16384
	s_cmp_ge_i32 s0, s51
	s_cbranch_scc1 .Lpa_nd3
	s_add_i32 m0, s1, 0x6000
	s_nop 0
	global_load_lds_dwordx4 v178, s[34:35]
.Lpa_nd3:
	s_waitcnt lgkmcnt(7)
	v_mfma_f32_32x32x16_bf16 v[80:95], v[210:213], v[140:143], v[80:95]
	ds_read_b128 v[210:213], v181 offset:20480
	s_waitcnt lgkmcnt(7)
	v_mfma_f32_32x32x16_bf16 v[96:111], v[182:185], v[144:147], v[96:111]
	ds_read_b128 v[182:185], v14 offset:24576
	s_waitcnt lgkmcnt(7)
	v_mfma_f32_32x32x16_bf16 v[80:95], v[186:189], v[144:147], v[80:95]
	ds_read_b128 v[186:189], v14 offset:28672
	s_waitcnt lgkmcnt(7)
	v_mfma_f32_32x32x16_bf16 v[96:111], v[190:193], v[148:151], v[96:111]
	ds_read_b128 v[190:193], v14 offset:32768
	s_cmp_ge_i32 s0, s51
	s_cbranch_scc1 .Lpa_nd4
	v_add_u32_e32 v2, 0x200000, v178
	s_add_i32 m0, s1, 0x8000
	s_nop 0
	global_load_lds_dwordx4 v2, s[34:35]
	v_add_u32_e32 v178, 0x80, v178
.Lpa_nd4:
	s_waitcnt lgkmcnt(7)
	v_mfma_f32_32x32x16_bf16 v[80:95], v[194:197], v[148:151], v[80:95]
	ds_read_b128 v[194:197], v14 offset:36864
	s_waitcnt lgkmcnt(7)
	v_mfma_f32_32x32x16_bf16 v[96:111], v[198:201], v[152:155], v[96:111]
	ds_read_b128 v[198:201], v15 offset:24576
	s_waitcnt lgkmcnt(7)
	v_mfma_f32_32x32x16_bf16 v[80:95], v[202:205], v[152:155], v[80:95]
	ds_read_b128 v[202:205], v15 offset:28672
	s_waitcnt lgkmcnt(7)
	v_mfma_f32_32x32x16_bf16 v[96:111], v[206:209], v[156:159], v[96:111]
	ds_read_b128 v[206:209], v15 offset:32768
	s_waitcnt lgkmcnt(7)
	v_mfma_f32_32x32x16_bf16 v[80:95], v[210:213], v[156:159], v[80:95]
	ds_read_b128 v[210:213], v15 offset:36864
	s_mov_b32 s0, 0xff800000
	s_nop 7
	v_max3_f32 v2, v96, s0, v97
	v_max3_f32 v2, v2, v98, v99
	v_max3_f32 v2, v2, v100, v101
	v_max3_f32 v2, v2, v102, v103
	v_max3_f32 v2, v2, v104, v105
	v_max3_f32 v2, v2, v106, v107
	v_max3_f32 v2, v2, v108, v109
	v_max3_f32 v2, v2, v110, v111
	v_max3_f32 v3, v80, s0, v81
	v_max3_f32 v3, v3, v82, v83
	v_max3_f32 v3, v3, v84, v85
	v_max3_f32 v3, v3, v86, v87
	v_max3_f32 v3, v3, v88, v89
	v_max3_f32 v3, v3, v90, v91
	v_max3_f32 v3, v3, v92, v93
	v_max3_f32 v3, v3, v94, v95
	v_max_f32_e32 v2, v2, v3
	ds_bpermute_b32 v3, v164, v2
	s_mov_b32 s0, 0x41000000
	s_waitcnt lgkmcnt(0)
	v_max_f32_e32 v3, v3, v3
	v_max_f32_e32 v2, v2, v3
	v_cmp_lt_f32_e32 vcc, s0, v2
	s_cbranch_vccz .Lpa_nors
	v_max_f32_e32 v2, v2, v2
	v_max_f32_e32 v2, 0, v2
	v_exp_f32_e64 v4, -v2
	v_add_f32_e32 v179, v179, v2
	v_pk_add_f32 v[96:97], v[96:97], v[2:3] op_sel_hi:[1,0] neg_lo:[0,1] neg_hi:[0,1]
	v_pk_add_f32 v[98:99], v[98:99], v[2:3] op_sel_hi:[1,0] neg_lo:[0,1] neg_hi:[0,1]
	v_pk_add_f32 v[100:101], v[100:101], v[2:3] op_sel_hi:[1,0] neg_lo:[0,1] neg_hi:[0,1]
	v_pk_add_f32 v[102:103], v[102:103], v[2:3] op_sel_hi:[1,0] neg_lo:[0,1] neg_hi:[0,1]
	v_pk_add_f32 v[104:105], v[104:105], v[2:3] op_sel_hi:[1,0] neg_lo:[0,1] neg_hi:[0,1]
	v_pk_add_f32 v[106:107], v[106:107], v[2:3] op_sel_hi:[1,0] neg_lo:[0,1] neg_hi:[0,1]
	v_pk_add_f32 v[108:109], v[108:109], v[2:3] op_sel_hi:[1,0] neg_lo:[0,1] neg_hi:[0,1]
	v_pk_add_f32 v[110:111], v[110:111], v[2:3] op_sel_hi:[1,0] neg_lo:[0,1] neg_hi:[0,1]
	v_pk_add_f32 v[80:81], v[80:81], v[2:3] op_sel_hi:[1,0] neg_lo:[0,1] neg_hi:[0,1]
	v_pk_add_f32 v[82:83], v[82:83], v[2:3] op_sel_hi:[1,0] neg_lo:[0,1] neg_hi:[0,1]
	v_pk_add_f32 v[84:85], v[84:85], v[2:3] op_sel_hi:[1,0] neg_lo:[0,1] neg_hi:[0,1]
	v_pk_add_f32 v[86:87], v[86:87], v[2:3] op_sel_hi:[1,0] neg_lo:[0,1] neg_hi:[0,1]
	v_pk_add_f32 v[88:89], v[88:89], v[2:3] op_sel_hi:[1,0] neg_lo:[0,1] neg_hi:[0,1]
	v_pk_add_f32 v[90:91], v[90:91], v[2:3] op_sel_hi:[1,0] neg_lo:[0,1] neg_hi:[0,1]
	v_pk_add_f32 v[92:93], v[92:93], v[2:3] op_sel_hi:[1,0] neg_lo:[0,1] neg_hi:[0,1]
	v_pk_add_f32 v[94:95], v[94:95], v[2:3] op_sel_hi:[1,0] neg_lo:[0,1] neg_hi:[0,1]
	v_pk_mul_f32 v[78:79], v[78:79], v[4:5] op_sel_hi:[1,0]
	v_pk_mul_f32 v[76:77], v[76:77], v[4:5] op_sel_hi:[1,0]
	v_pk_mul_f32 v[74:75], v[74:75], v[4:5] op_sel_hi:[1,0]
	v_pk_mul_f32 v[72:73], v[72:73], v[4:5] op_sel_hi:[1,0]
	v_pk_mul_f32 v[70:71], v[70:71], v[4:5] op_sel_hi:[1,0]
	v_pk_mul_f32 v[68:69], v[68:69], v[4:5] op_sel_hi:[1,0]
	v_pk_mul_f32 v[66:67], v[66:67], v[4:5] op_sel_hi:[1,0]
	v_pk_mul_f32 v[64:65], v[64:65], v[4:5] op_sel_hi:[1,0]
	v_pk_mul_f32 v[62:63], v[62:63], v[4:5] op_sel_hi:[1,0]
	v_pk_mul_f32 v[60:61], v[60:61], v[4:5] op_sel_hi:[1,0]
	v_pk_mul_f32 v[58:59], v[58:59], v[4:5] op_sel_hi:[1,0]
	v_pk_mul_f32 v[56:57], v[56:57], v[4:5] op_sel_hi:[1,0]
	v_pk_mul_f32 v[54:55], v[54:55], v[4:5] op_sel_hi:[1,0]
	v_pk_mul_f32 v[52:53], v[52:53], v[4:5] op_sel_hi:[1,0]
	v_pk_mul_f32 v[50:51], v[50:51], v[4:5] op_sel_hi:[1,0]
	v_pk_mul_f32 v[48:49], v[48:49], v[4:5] op_sel_hi:[1,0]
	v_pk_mul_f32 v[46:47], v[46:47], v[4:5] op_sel_hi:[1,0]
	v_pk_mul_f32 v[44:45], v[44:45], v[4:5] op_sel_hi:[1,0]
	v_pk_mul_f32 v[42:43], v[42:43], v[4:5] op_sel_hi:[1,0]
	v_pk_mul_f32 v[40:41], v[40:41], v[4:5] op_sel_hi:[1,0]
	v_pk_mul_f32 v[38:39], v[38:39], v[4:5] op_sel_hi:[1,0]
	v_pk_mul_f32 v[36:37], v[36:37], v[4:5] op_sel_hi:[1,0]
	v_pk_mul_f32 v[34:35], v[34:35], v[4:5] op_sel_hi:[1,0]
	v_pk_mul_f32 v[32:33], v[32:33], v[4:5] op_sel_hi:[1,0]
	v_pk_mul_f32 v[30:31], v[30:31], v[4:5] op_sel_hi:[1,0]
	v_pk_mul_f32 v[28:29], v[28:29], v[4:5] op_sel_hi:[1,0]
	v_pk_mul_f32 v[26:27], v[26:27], v[4:5] op_sel_hi:[1,0]
	v_pk_mul_f32 v[24:25], v[24:25], v[4:5] op_sel_hi:[1,0]
	v_pk_mul_f32 v[22:23], v[22:23], v[4:5] op_sel_hi:[1,0]
	v_pk_mul_f32 v[20:21], v[20:21], v[4:5] op_sel_hi:[1,0]
	v_pk_mul_f32 v[18:19], v[18:19], v[4:5] op_sel_hi:[1,0]
	v_pk_mul_f32 v[16:17], v[16:17], v[4:5] op_sel_hi:[1,0]
	v_mul_f32_e32 v171, v171, v4

.Lpa_978b:
	s_add_i32 s0, s52, 1
	s_cmp_lg_u32 s52, 2
	s_cselect_b32 s52, s0, 0
	s_cmp_eq_u32 s50, s53
	v_readlane_b32 s89, v243, 20
	s_cbranch_scc1 .LBB0_983
	s_mov_b32 s0, s53
	s_add_i32 s53, s0, 1
	s_cmp_ge_i32 s53, s50
	s_mov_b64 s[36:37], -1
	s_cbranch_scc1 .LBB0_969
	s_branch .LBB0_970
.Lpa_masked:
	s_or_b64 exec, exec, s[36:37]
	s_cmp_ge_i32 s0, s51
	s_cbranch_scc1 .Lpa_978b
	s_add_i32 s36, s1, 0xffff6000
	s_cmp_lg_u32 s52, 0
	s_cselect_b32 s36, s36, 0x14000
	v_add_u32_e32 v4, s36, v170
	v_add_u32_e32 v5, 0x2000, v4
	v_readfirstlane_b32 s36, v4
	v_lshl_add_u64 v[2:3], s[30:31], 0, v[0:1]
	s_mov_b32 m0, s36
	v_readfirstlane_b32 s36, v5
	global_load_lds_dwordx4 v0, s[30:31]
	v_lshl_add_u64 v[2:3], v[2:3], 0, s[54:55]
	s_mov_b32 m0, s36
	v_add_u32_e32 v0, 0x20000, v0
	global_load_lds_dwordx4 v[2:3], off
	v_add_u32_e32 v2, 0x4000, v4
	v_add_u32_e32 v3, 0x8000, v4
	v_readfirstlane_b32 s36, v2
	v_add_u32_e32 v2, 0x6000, v4
	s_mov_b32 m0, s36
	v_readfirstlane_b32 s36, v2
	global_load_lds_dwordx4 v177, s[12:13]
	s_mov_b32 m0, s36
	v_readfirstlane_b32 s36, v3
	global_load_lds_dwordx4 v178, s[34:35]
	v_add_u32_e32 v2, 0x200000, v178
	s_mov_b32 m0, s36
	v_add_u32_e32 v177, 0x2000, v177
	global_load_lds_dwordx4 v2, s[34:35]
	v_add_u32_e32 v178, 0x80, v178
	s_branch .Lpa_978b

.LBB0_987:
	v_exp_f32_e32 v80, v80
	v_exp_f32_e32 v81, v81
	v_exp_f32_e32 v82, v82
	v_exp_f32_e32 v83, v83
	v_add_f32_e32 v5, 0, v80
	v_exp_f32_e32 v84, v84
	v_add_f32_e32 v5, v81, v5
	v_exp_f32_e32 v85, v85
	v_add_f32_e32 v5, v82, v5
	v_exp_f32_e32 v86, v86
	v_add_f32_e32 v5, v83, v5
	v_exp_f32_e32 v87, v87
	v_add_f32_e32 v5, v84, v5
	v_exp_f32_e32 v88, v88
	v_add_f32_e32 v5, v85, v5
	v_exp_f32_e32 v89, v89
	v_add_f32_e32 v5, v86, v5
	v_exp_f32_e32 v90, v90
	v_add_f32_e32 v5, v87, v5
	v_exp_f32_e32 v91, v91
	v_add_f32_e32 v5, v88, v5
	v_exp_f32_e32 v92, v92
	v_add_f32_e32 v5, v89, v5
	v_exp_f32_e32 v93, v93
	v_add_f32_e32 v5, v90, v5
	v_exp_f32_e32 v94, v94
	v_add_f32_e32 v5, v91, v5
	v_exp_f32_e32 v95, v95
	v_add_f32_e32 v5, v92, v5
	v_add_f32_e32 v5, v93, v5
	v_add_f32_e32 v5, v94, v5
	v_add_f32_e32 v5, v95, v5
	v_cvt_pk_bf16_f32 v6, v80, v81
	v_cvt_pk_bf16_f32 v7, v82, v83
	v_cvt_pk_bf16_f32 v8, v84, v85
	v_cvt_pk_bf16_f32 v9, v86, v87
	v_cvt_pk_bf16_f32 v10, v88, v89
	v_cvt_pk_bf16_f32 v11, v90, v91
	v_cvt_pk_bf16_f32 v12, v92, v93
	v_cvt_pk_bf16_f32 v13, v94, v95
	v_add_f32_e32 v2, v2, v5
	s_nop 0
	v_mfma_f32_32x32x16_bf16 v[64:79], v[206:209], v[6:9], v[64:79]
	v_mfma_f32_32x32x16_bf16 v[48:63], v[210:213], v[6:9], v[48:63]
	v_mfma_f32_32x32x16_bf16 v[32:47], v[214:217], v[6:9], v[32:47]
	v_mfma_f32_32x32x16_bf16 v[16:31], v[218:221], v[6:9], v[16:31]
	v_mfma_f32_32x32x16_bf16 v[64:79], v[222:225], v[10:13], v[64:79]
	v_mfma_f32_32x32x16_bf16 v[48:63], v[226:229], v[10:13], v[48:63]
	v_mfma_f32_32x32x16_bf16 v[32:47], v[230:233], v[10:13], v[32:47]
	v_mfma_f32_32x32x16_bf16 v[16:31], v[234:237], v[10:13], v[16:31]

.LBB0_995:
	s_and_saveexec_b64 s[48:49], s[6:7]
	s_cbranch_execz .LBB0_988
	v_add_u32_e32 v3, s1, v155
	v_add_u32_e32 v8, v3, v160
	v_add_u32_e32 v9, v8, v151
	ds_read_b128 v[182:185], v9
	v_add_u32_e32 v10, v8, v152
	ds_read_b128 v[186:189], v10
	v_add_u32_e32 v11, v8, v153
	ds_read_b128 v[190:193], v11
	v_add_u32_e32 v12, v8, v154
	ds_read_b128 v[194:197], v12
	ds_read_b128 v[198:201], v9 offset:8192
	ds_read_b128 v[202:205], v10 offset:8192
	v_add_u32_e32 v238, v3, v156
	v_add_u32_e32 v239, v3, v157
	v_xor_b32_e32 v80, 0x80000000, v148
	v_mov_b32_e32 v81, v80
	v_mov_b32_e32 v82, v80
	v_mov_b32_e32 v83, v80
	v_mov_b32_e32 v84, v80
	v_mov_b32_e32 v85, v80
	v_mov_b32_e32 v86, v80
	v_mov_b32_e32 v87, v80
	v_mov_b32_e32 v88, v80
	v_mov_b32_e32 v89, v80
	v_mov_b32_e32 v90, v80
	v_mov_b32_e32 v91, v80
	v_mov_b32_e32 v92, v80
	v_mov_b32_e32 v93, v80
	v_mov_b32_e32 v94, v80
	v_mov_b32_e32 v95, v80
	s_nop 1
	s_waitcnt lgkmcnt(5)
	v_mfma_f32_32x32x16_bf16 v[80:95], v[182:185], v[96:99], v[80:95]
	ds_read_b128 v[182:185], v11 offset:8192
	s_waitcnt lgkmcnt(5)
	v_mfma_f32_32x32x16_bf16 v[80:95], v[186:189], v[100:103], v[80:95]
	ds_read_b128 v[186:189], v12 offset:8192
	s_waitcnt lgkmcnt(5)
	v_mfma_f32_32x32x16_bf16 v[80:95], v[190:193], v[104:107], v[80:95]
	ds_read_b128 v[190:193], v9 offset:16384
	s_waitcnt lgkmcnt(5)
	v_mfma_f32_32x32x16_bf16 v[80:95], v[194:197], v[108:111], v[80:95]
	ds_read_b128 v[194:197], v10 offset:16384
	s_waitcnt lgkmcnt(5)
	v_mfma_f32_32x32x16_bf16 v[80:95], v[198:201], v[112:115], v[80:95]
	ds_read_b128 v[198:201], v11 offset:16384
	s_waitcnt lgkmcnt(5)
	v_mfma_f32_32x32x16_bf16 v[80:95], v[202:205], v[116:119], v[80:95]
	ds_read_b128 v[202:205], v12 offset:16384
	s_waitcnt lgkmcnt(5)
	v_mfma_f32_32x32x16_bf16 v[80:95], v[182:185], v[120:123], v[80:95]
	ds_read_b128 v[206:209], v238 offset:24576
	s_waitcnt lgkmcnt(5)
	v_mfma_f32_32x32x16_bf16 v[80:95], v[186:189], v[124:127], v[80:95]
	ds_read_b128 v[210:213], v238 offset:28672
	s_waitcnt lgkmcnt(5)
	v_mfma_f32_32x32x16_bf16 v[80:95], v[190:193], v[128:131], v[80:95]
	ds_read_b128 v[214:217], v238 offset:32768
	s_waitcnt lgkmcnt(5)
	v_mfma_f32_32x32x16_bf16 v[80:95], v[194:197], v[132:135], v[80:95]
	ds_read_b128 v[218:221], v238 offset:36864
	s_waitcnt lgkmcnt(5)
	v_mfma_f32_32x32x16_bf16 v[80:95], v[198:201], v[136:139], v[80:95]
	ds_read_b128 v[222:225], v239 offset:24576
	s_waitcnt lgkmcnt(5)
	v_mfma_f32_32x32x16_bf16 v[80:95], v[202:205], v[140:143], v[80:95]
	ds_read_b128 v[226:229], v239 offset:28672
	ds_read_b128 v[230:233], v239 offset:32768
	ds_read_b128 v[234:237], v239 offset:36864
	s_andn2_b64 vcc, exec, s[50:51]
	s_cbranch_vccnz .LBB0_998
	s_nop 9
	v_mov_b32_e32 v88, 0xff800000
	v_cndmask_b32_e64 v80, v88, v80, s[8:9]
	v_cndmask_b32_e64 v81, v88, v81, s[8:9]
	v_cndmask_b32_e64 v82, v88, v82, s[8:9]
	v_cndmask_b32_e64 v83, v88, v83, s[8:9]
	v_cndmask_b32_e64 v84, v88, v84, s[8:9]
	v_cndmask_b32_e64 v85, v88, v85, s[8:9]
	v_cndmask_b32_e64 v86, v88, v86, s[8:9]
	v_cndmask_b32_e64 v87, v88, v87, s[8:9]
	v_mov_b32_e32 v89, v88
	v_mov_b32_e32 v90, v88
	v_mov_b32_e32 v91, v88
	v_mov_b32_e32 v92, v88
	v_mov_b32_e32 v93, v88
	v_mov_b32_e32 v94, v88
	v_mov_b32_e32 v95, v88
